# MLA w_in phase rebalanced: the 160 GEMM workgroups each convert one weight tile after their unit, pure converters get 11 percent fewer (plus pipelined conversion)
# speedup vs baseline: 1.0028x; 1.0028x over previous
.LBB0_299:
	s_abs_i32 s6, s80
	v_cvt_f32_u32_e32 v0, s6
	s_sub_i32 s7, 0, s6
	v_rcp_iflag_f32_e32 v0, v0
	s_nop 0
	v_mul_f32_e32 v0, 0x4f7ffffe, v0
	v_cvt_u32_f32_e32 v0, v0
	s_nop 0
	v_readfirstlane_b32 s8, v0
	s_mul_i32 s7, s7, s8
	s_mul_hi_u32 s7, s8, s7
	s_add_i32 s8, s8, s7
	s_mul_hi_u32 s7, s8, 0xa0
	s_mul_i32 s7, s7, s6
	s_sub_i32 s7, 0xa0, s7
	s_sub_i32 s8, s7, s6
	s_cmp_ge_u32 s7, s6
	s_cselect_b32 s7, s8, s7
	s_sub_i32 s8, s7, s6
	s_cmp_ge_u32 s7, s6
	s_cselect_b32 s6, s8, s7
	s_cmp_lt_i32 s81, s6
	s_cbranch_scc1 .Lg5_helper
	s_ashr_i32 s7, s82, 6
	s_mul_i32 s8, s76, 0xab40
	s_sub_i32 s9, s81, s6
	s_add_i32 s18, s8, 0x9040
	s_lshl_b32 s9, s9, 3
	s_add_i32 s8, s8, s7
	s_add_i32 s8, s8, s9
	s_add_i32 s19, s8, 0x6940
	s_cmp_ge_i32 s19, s18
	s_cbranch_scc1 .LBB0_360
	s_sub_i32 s6, s80, s6
	s_lshl_b32 s20, s6, 3
.Lg5_join:
	s_lshl_b32 s6, s7, 14
	s_add_i32 s6, s6, 0
	s_add_u32 s21, s10, 0x10612000
	s_addc_u32 s22, s11, 0
	s_add_u32 s23, s10, 0x5612000
	s_addc_u32 s24, s11, 0
	s_add_u32 s25, s10, 0x4612000
	s_addc_u32 s26, s11, 0
	s_add_u32 s27, s10, 0x3e12000
	s_addc_u32 s28, s11, 0
	s_add_u32 s29, s10, 0x3812000
	s_addc_u32 s30, s11, 0
	s_add_u32 s31, s10, 0x1e12000
	v_bfe_u32 v10, v188, 3, 3
	s_addc_u32 s33, s11, 0
	v_lshlrev_b32_e32 v0, 2, v188
	v_and_b32_e32 v3, 7, v188
	v_lshlrev_b32_e32 v6, 2, v10
	s_add_u32 s34, s10, 0x612000
	v_and_b32_e32 v0, 28, v0
	v_lshl_add_u32 v4, v3, 4, s6
	v_mul_u32_u24_e32 v5, 0x84, v10
	v_lshlrev_b32_e32 v2, 3, v3
	v_mul_u32_u24_e32 v3, 0x420, v3
	v_and_b32_e32 v14, 16, v6
	s_addc_u32 s35, s11, 0
	v_or_b32_e32 v11, 8, v10
	v_or_b32_e32 v12, 16, v10
	v_or_b32_e32 v13, 24, v10
	v_add3_u32 v15, s6, v3, v6
	v_or_b32_e32 v16, 4, v14
	v_or_b32_e32 v17, 8, v14
	v_or_b32_e32 v18, 12, v6
	v_lshlrev_b32_e32 v0, 2, v0
	v_add_u32_e32 v19, v4, v5
	v_lshlrev_b32_e32 v6, 1, v2
	s_mov_b32 s99, 0
	s_branch .LBB0_304
.Lg5_helper:
	s_waitcnt lgkmcnt(0)
	s_barrier
	s_ashr_i32 s7, s82, 6
	s_mul_i32 s8, s76, 0xab40
	s_add_i32 s18, s8, 0x9540
	s_lshl_b32 s9, s81, 3
	s_add_i32 s8, s8, s7
	s_add_i32 s8, s8, s9
	s_add_i32 s19, s8, 0x9040
	s_movk_i32 s20, 0x1000
	s_branch .Lg5_join
